# S5 item: the KT-table copy loop (load, wait, LDS write; 4-5 serial global round trips) replaced by five loads in flight followed by the LDS writes
# baseline (speedup 1.0000x reference)
.LBB0_734:
	global_load_dwordx4 v[142:145], v[138:139], off
	v_lshl_add_u64 v[138:139], v[138:139], 0, s[42:43]
	global_load_dwordx4 v[146:149], v[138:139], off
	v_lshl_add_u64 v[138:139], v[138:139], 0, s[42:43]
	global_load_dwordx4 v[150:153], v[138:139], off
	v_lshl_add_u64 v[138:139], v[138:139], 0, s[42:43]
	global_load_dwordx4 v[154:157], v[138:139], off
	v_lshl_add_u64 v[138:139], v[138:139], 0, s[42:43]
	v_cmp_gt_u32_e32 vcc, 32, v2
	s_and_saveexec_b64 s[12:13], vcc
	global_load_dwordx4 v[158:161], v[138:139], off
	s_mov_b64 exec, s[12:13]
	s_waitcnt vmcnt(4)
	ds_write_b128 v141, v[142:145]
	s_waitcnt vmcnt(3)
	ds_write_b128 v141, v[146:149] offset:8192
	s_waitcnt vmcnt(2)
	ds_write_b128 v141, v[150:153] offset:16384
	s_waitcnt vmcnt(1)
	ds_write_b128 v141, v[154:157] offset:24576
	s_waitcnt vmcnt(0)
	s_and_saveexec_b64 s[12:13], vcc
	ds_write_b128 v141, v[158:161] offset:32768
	s_mov_b64 exec, s[12:13]
